# adaLN task main loop hand-pipelined (rolling 56-load w_ada window, first window issued after the silu staging, before the barrier)
# baseline (speedup 1.0000x reference)
.LBB0_77:
	v_add_u32_e32 v2, s26, v1
	v_ashrrev_i32_e32 v3, 8, v2
	v_add_u32_e32 v4, 0x200, v2
	v_add_u32_e32 v5, 0x400, v2
	v_add_u32_e32 v6, 0x600, v2
	v_add_u32_e32 v7, 0x800, v2
	v_add_u32_e32 v8, 0xa00, v2
	v_add_u32_e32 v9, 0xc00, v2
	v_add_u32_e32 v10, 0xe00, v2
	v_add_u32_e32 v11, 0x1000, v2
	v_add_u32_e32 v12, 0x1200, v2
	v_add_u32_e32 v13, 0x1400, v2
	v_add_u32_e32 v2, 0x1600, v2
	v_add_u32_e32 v14, s24, v3
	v_ashrrev_i32_e32 v4, 8, v4
	v_ashrrev_i32_e32 v5, 8, v5
	v_ashrrev_i32_e32 v6, 8, v6
	v_ashrrev_i32_e32 v7, 8, v7
	v_ashrrev_i32_e32 v8, 8, v8
	v_ashrrev_i32_e32 v9, 8, v9
	v_ashrrev_i32_e32 v10, 8, v10
	v_ashrrev_i32_e32 v11, 8, v11
	v_ashrrev_i32_e32 v2, 8, v2
	v_min_i32_e32 v15, 0x81, v14
	v_ashrrev_i32_e32 v12, 8, v12
	v_mad_i32_i24 v23, v3, s27, v22
	v_add_u32_e32 v16, s24, v4
	v_add_u32_e32 v17, s24, v5
	v_add_u32_e32 v24, s24, v6
	v_add_u32_e32 v25, s24, v7
	v_add_u32_e32 v26, s24, v8
	v_add_u32_e32 v27, s24, v9
	v_add_u32_e32 v28, s24, v10
	v_add_u32_e32 v29, s24, v11
	v_add_u32_e32 v32, s24, v2
	v_mad_i32_i24 v82, v2, s27, v22
	v_add_u32_e32 v2, -2, v15
	v_ashrrev_i32_e32 v3, 31, v15
	v_cmp_gt_i32_e32 vcc, 2, v14
	v_ashrrev_i32_e32 v13, 8, v13
	v_add_u32_e32 v30, s24, v12
	v_mad_i32_i24 v74, v6, s27, v22
	v_mad_i32_i24 v76, v8, s27, v22
	v_mad_i32_i24 v78, v10, s27, v22
	v_mad_i32_i24 v80, v12, s27, v22
	v_min_i32_e32 v6, 0x81, v16
	v_min_i32_e32 v8, 0x81, v17
	v_min_i32_e32 v10, 0x81, v24
	v_min_i32_e32 v12, 0x81, v25
	v_min_i32_e32 v33, 0x81, v26
	v_min_i32_e32 v34, 0x81, v27
	v_min_i32_e32 v35, 0x81, v28
	v_min_i32_e32 v36, 0x81, v29
	v_cndmask_b32_e32 v3, 0, v3, vcc
	v_cndmask_b32_e32 v2, v2, v15, vcc
	s_waitcnt vmcnt(0)
	v_cndmask_b32_e64 v18, 24, 16, vcc
	v_cmp_gt_i32_e32 vcc, 2, v16
	v_add_u32_e32 v31, s24, v13
	v_mad_i32_i24 v72, v4, s27, v22
	v_mad_i32_i24 v73, v5, s27, v22
	v_mad_i32_i24 v77, v9, s27, v22
	v_mad_i32_i24 v79, v11, s27, v22
	v_mad_i32_i24 v81, v13, s27, v22
	v_min_i32_e32 v37, 0x81, v30
	v_add_u32_e32 v9, -2, v6
	v_ashrrev_i32_e32 v11, 31, v8
	v_cmp_gt_i32_e64 s[4:5], 2, v17
	v_add_u32_e32 v13, -2, v8
	v_ashrrev_i32_e32 v14, 31, v10
	v_cmp_gt_i32_e64 s[6:7], 2, v24
	v_add_u32_e32 v15, -2, v10
	v_ashrrev_i32_e32 v16, 31, v12
	v_cmp_gt_i32_e64 s[8:9], 2, v25
	v_add_u32_e32 v17, -2, v12
	v_ashrrev_i32_e32 v24, 31, v33
	v_cmp_gt_i32_e64 s[10:11], 2, v26
	v_add_u32_e32 v25, -2, v33
	v_ashrrev_i32_e32 v26, 31, v34
	v_cmp_gt_i32_e64 s[12:13], 2, v27
	v_add_u32_e32 v27, -2, v34
	v_ashrrev_i32_e32 v40, 31, v35
	v_cmp_gt_i32_e64 s[14:15], 2, v28
	v_add_u32_e32 v28, -2, v35
	v_add_u32_e32 v41, -2, v36
	v_ashrrev_i32_e32 v42, 31, v36
	v_cmp_gt_i32_e64 s[16:17], 2, v29
	v_lshl_add_u64 v[4:5], s[0:1], 0, v[18:19]
	v_cndmask_b32_e64 v18, 24, 16, vcc
	v_mad_i32_i24 v75, v7, s27, v22
	v_min_i32_e32 v39, 0x81, v32
	v_ashrrev_i32_e32 v7, 31, v6
	v_add_u32_e32 v43, -2, v37
	v_ashrrev_i32_e32 v29, 31, v37
	v_cmp_gt_i32_e64 s[18:19], 2, v30
	v_cndmask_b32_e32 v6, v9, v6, vcc
	v_cndmask_b32_e64 v9, 0, v11, s[4:5]
	v_cndmask_b32_e64 v8, v13, v8, s[4:5]
	v_cndmask_b32_e64 v11, 0, v14, s[6:7]
	v_cndmask_b32_e64 v10, v15, v10, s[6:7]
	v_cndmask_b32_e64 v13, 0, v16, s[8:9]
	v_cndmask_b32_e64 v12, v17, v12, s[8:9]
	v_cndmask_b32_e64 v15, 0, v24, s[10:11]
	v_cndmask_b32_e64 v14, v25, v33, s[10:11]
	v_cndmask_b32_e64 v17, 0, v26, s[12:13]
	v_cndmask_b32_e64 v16, v27, v34, s[12:13]
	v_cndmask_b32_e64 v25, 0, v40, s[14:15]
	v_cndmask_b32_e64 v24, v28, v35, s[14:15]
	v_cndmask_b32_e64 v27, 0, v42, s[16:17]
	v_cndmask_b32_e64 v26, v41, v36, s[16:17]
	global_load_dwordx2 v[4:5], v[4:5], off
	v_lshl_add_u64 v[34:35], s[0:1], 0, v[18:19]
	v_cndmask_b32_e64 v18, 24, 16, s[4:5]
	v_add_u32_e32 v45, -2, v39
	v_ashrrev_i32_e32 v46, 31, v39
	v_cmp_gt_i32_e64 s[22:23], 2, v32
	v_cndmask_b32_e64 v29, 0, v29, s[18:19]
	v_cndmask_b32_e64 v28, v43, v37, s[18:19]
	v_lshlrev_b64 v[48:49], 12, v[24:25]
	v_lshlrev_b64 v[52:53], 12, v[26:27]
	global_load_dwordx2 v[24:25], v[34:35], off
	v_lshl_add_u64 v[26:27], s[0:1], 0, v[18:19]
	v_cndmask_b32_e64 v18, 24, 16, s[6:7]
	v_cndmask_b32_e64 v33, 0, v46, s[22:23]
	v_cndmask_b32_e64 v32, v45, v39, s[22:23]
	v_lshlrev_b64 v[54:55], 12, v[28:29]
	global_load_dwordx2 v[28:29], v[26:27], off
	v_lshl_add_u64 v[26:27], s[0:1], 0, v[18:19]
	v_cndmask_b32_e64 v18, 24, 16, s[8:9]
	v_lshlrev_b64 v[58:59], 12, v[32:33]
	global_load_dwordx2 v[32:33], v[26:27], off
	v_lshl_add_u64 v[26:27], s[0:1], 0, v[18:19]
	v_cndmask_b32_e64 v18, 24, 16, s[10:11]
	v_min_i32_e32 v38, 0x81, v31
	global_load_dwordx2 v[36:37], v[26:27], off
	v_lshl_add_u64 v[26:27], s[0:1], 0, v[18:19]
	v_cndmask_b32_e64 v18, 24, 16, s[12:13]
	v_ashrrev_i32_e32 v44, 31, v38
	v_cmp_gt_i32_e64 s[20:21], 2, v31
	global_load_dwordx2 v[40:41], v[26:27], off
	v_lshl_add_u64 v[26:27], s[0:1], 0, v[18:19]
	v_cndmask_b32_e64 v18, 24, 16, s[14:15]
	v_cndmask_b32_e64 v31, 0, v44, s[20:21]
	global_load_dwordx2 v[44:45], v[26:27], off
	v_lshl_add_u64 v[26:27], s[0:1], 0, v[18:19]
	v_cndmask_b32_e64 v18, 24, 16, s[16:17]
	global_load_dwordx2 v[50:51], v[26:27], off
	v_lshl_add_u64 v[26:27], s[0:1], 0, v[18:19]
	v_cndmask_b32_e64 v18, 24, 16, s[18:19]
	global_load_dwordx2 v[60:61], v[26:27], off
	v_lshl_add_u64 v[26:27], s[0:1], 0, v[18:19]
	v_cndmask_b32_e64 v18, 24, 16, s[20:21]
	global_load_dwordx2 v[62:63], v[26:27], off
	v_lshl_add_u64 v[26:27], s[0:1], 0, v[18:19]
	v_cndmask_b32_e64 v18, 24, 16, s[22:23]
	global_load_dwordx2 v[64:65], v[26:27], off
	v_lshl_add_u64 v[26:27], s[0:1], 0, v[18:19]
	global_load_dwordx2 v[66:67], v[26:27], off
	v_lshlrev_b64 v[2:3], 12, v[2:3]
	v_cndmask_b32_e32 v7, 0, v7, vcc
	v_lshlrev_b64 v[6:7], 12, v[6:7]
	v_add_u32_e32 v30, -2, v38
	v_lshlrev_b64 v[8:9], 12, v[8:9]
	v_cndmask_b32_e64 v30, v30, v38, s[20:21]
	v_lshlrev_b64 v[10:11], 12, v[10:11]
	v_lshlrev_b64 v[12:13], 12, v[12:13]
	v_lshlrev_b64 v[56:57], 12, v[30:31]
	v_lshlrev_b64 v[14:15], 12, v[14:15]
	v_lshlrev_b64 v[16:17], 12, v[16:17]
	s_addk_i32 s26, 0x1800
	s_cmpk_eq_i32 s26, 0x3000
	s_waitcnt vmcnt(11)
	v_lshl_add_u64 v[2:3], v[4:5], 0, v[2:3]
	v_lshl_add_u64 v[2:3], v[2:3], 0, v[20:21]
	s_waitcnt vmcnt(10)
	v_lshl_add_u64 v[4:5], v[24:25], 0, v[6:7]
	global_load_dwordx4 v[24:27], v[2:3], off
	v_lshl_add_u64 v[2:3], v[4:5], 0, v[20:21]
	s_waitcnt vmcnt(10)
	v_lshl_add_u64 v[4:5], v[28:29], 0, v[8:9]
	global_load_dwordx4 v[28:31], v[2:3], off
	v_lshl_add_u64 v[2:3], v[4:5], 0, v[20:21]
	s_waitcnt vmcnt(10)
	v_lshl_add_u64 v[4:5], v[32:33], 0, v[10:11]
	global_load_dwordx4 v[32:35], v[2:3], off
	v_lshl_add_u64 v[2:3], v[4:5], 0, v[20:21]
	s_waitcnt vmcnt(10)
	v_lshl_add_u64 v[4:5], v[36:37], 0, v[12:13]
	global_load_dwordx4 v[36:39], v[2:3], off
	v_lshl_add_u64 v[2:3], v[4:5], 0, v[20:21]
	s_waitcnt vmcnt(10)
	v_lshl_add_u64 v[4:5], v[40:41], 0, v[14:15]
	global_load_dwordx4 v[40:43], v[2:3], off
	v_lshl_add_u64 v[2:3], v[4:5], 0, v[20:21]
	s_waitcnt vmcnt(10)
	v_lshl_add_u64 v[4:5], v[44:45], 0, v[16:17]
	global_load_dwordx4 v[44:47], v[2:3], off
	v_lshl_add_u64 v[2:3], v[4:5], 0, v[20:21]
	s_waitcnt vmcnt(10)
	v_lshl_add_u64 v[4:5], v[50:51], 0, v[48:49]
	global_load_dwordx4 v[48:51], v[2:3], off
	v_lshl_add_u64 v[4:5], v[4:5], 0, v[20:21]
	s_waitcnt vmcnt(10)
	v_lshl_add_u64 v[2:3], v[60:61], 0, v[52:53]
	v_lshl_add_u64 v[2:3], v[2:3], 0, v[20:21]
	global_load_dwordx4 v[10:13], v[2:3], off
	s_waitcnt vmcnt(10)
	v_lshl_add_u64 v[6:7], v[62:63], 0, v[54:55]
	global_load_dwordx4 v[52:55], v[4:5], off
	v_lshl_add_u64 v[2:3], v[6:7], 0, v[20:21]
	s_waitcnt vmcnt(10)
	v_lshl_add_u64 v[4:5], v[64:65], 0, v[56:57]
	global_load_dwordx4 v[14:17], v[2:3], off
	s_waitcnt vmcnt(10)
	v_lshl_add_u64 v[56:57], v[66:67], 0, v[58:59]
	v_lshl_add_u64 v[2:3], v[4:5], 0, v[20:21]
	global_load_dwordx4 v[6:9], v[2:3], off
	v_lshl_add_u64 v[2:3], v[56:57], 0, v[20:21]
	global_load_dwordx4 v[2:5], v[2:3], off
	s_waitcnt vmcnt(11)
	v_mul_f32_e32 v18, 0xbfb8aa3b, v24
	v_mul_f32_e32 v56, 0xbfb8aa3b, v25
	v_mul_f32_e32 v57, 0xbfb8aa3b, v26
	v_mul_f32_e32 v58, 0xbfb8aa3b, v27
	v_exp_f32_e32 v18, v18
	v_exp_f32_e32 v56, v56
	v_exp_f32_e32 v57, v57
	v_exp_f32_e32 v58, v58
	s_waitcnt vmcnt(10)
	v_mul_f32_e32 v59, 0xbfb8aa3b, v28
	v_mul_f32_e32 v60, 0xbfb8aa3b, v29
	v_mul_f32_e32 v61, 0xbfb8aa3b, v30
	v_mul_f32_e32 v62, 0xbfb8aa3b, v31
	v_exp_f32_e32 v63, v59
	v_exp_f32_e32 v60, v60
	v_exp_f32_e32 v61, v61
	v_exp_f32_e32 v62, v62
	s_waitcnt vmcnt(9)
	v_mul_f32_e32 v59, 0xbfb8aa3b, v32
	v_mul_f32_e32 v64, 0xbfb8aa3b, v33
	v_mul_f32_e32 v65, 0xbfb8aa3b, v34
	v_mul_f32_e32 v66, 0xbfb8aa3b, v35
	v_exp_f32_e32 v67, v59
	v_exp_f32_e32 v64, v64
	v_exp_f32_e32 v65, v65
	v_exp_f32_e32 v66, v66
	s_waitcnt vmcnt(8)
	v_mul_f32_e32 v59, 0xbfb8aa3b, v36
	v_mul_f32_e32 v68, 0xbfb8aa3b, v37
	v_mul_f32_e32 v69, 0xbfb8aa3b, v38
	v_mul_f32_e32 v70, 0xbfb8aa3b, v39
	v_exp_f32_e32 v71, v59
	v_exp_f32_e32 v68, v68
	v_exp_f32_e32 v69, v69
	v_exp_f32_e32 v70, v70
	s_waitcnt vmcnt(7)
	v_mul_f32_e32 v59, 0xbfb8aa3b, v40
	v_mul_f32_e32 v83, 0xbfb8aa3b, v41
	v_mul_f32_e32 v84, 0xbfb8aa3b, v42
	v_mul_f32_e32 v85, 0xbfb8aa3b, v43
	v_add_f32_e32 v18, 1.0, v18
	v_add_f32_e32 v87, 1.0, v56
	v_add_f32_e32 v88, 1.0, v57
	v_add_f32_e32 v89, 1.0, v58
	v_exp_f32_e32 v90, v59
	v_exp_f32_e32 v83, v83
	v_exp_f32_e32 v84, v84
	v_exp_f32_e32 v85, v85
	s_waitcnt vmcnt(6)
	v_mul_f32_e32 v91, 0xbfb8aa3b, v44
	v_mul_f32_e32 v92, 0xbfb8aa3b, v45
	v_mul_f32_e32 v93, 0xbfb8aa3b, v46
	v_mul_f32_e32 v94, 0xbfb8aa3b, v47
	v_rcp_f32_e32 v56, v18
	v_rcp_f32_e32 v57, v87
	v_rcp_f32_e32 v58, v88
	v_rcp_f32_e32 v59, v89
	v_add_f32_e32 v18, 1.0, v63
	v_add_f32_e32 v63, 1.0, v60
	v_add_f32_e32 v87, 1.0, v61
	v_add_f32_e32 v88, 1.0, v62
	v_exp_f32_e32 v89, v91
	v_exp_f32_e32 v91, v92
	v_exp_f32_e32 v92, v93
	v_exp_f32_e32 v93, v94
	s_waitcnt vmcnt(5)
	v_mul_f32_e32 v94, 0xbfb8aa3b, v48
	v_mul_f32_e32 v95, 0xbfb8aa3b, v49
	v_mul_f32_e32 v96, 0xbfb8aa3b, v50
	v_mul_f32_e32 v97, 0xbfb8aa3b, v51
	v_rcp_f32_e32 v60, v18
	v_rcp_f32_e32 v61, v63
	v_rcp_f32_e32 v62, v87
	v_rcp_f32_e32 v63, v88
	v_add_f32_e32 v18, 1.0, v67
	v_add_f32_e32 v67, 1.0, v64
	v_add_f32_e32 v87, 1.0, v65
	v_add_f32_e32 v88, 1.0, v66
	v_exp_f32_e32 v94, v94
	v_exp_f32_e32 v95, v95
	v_exp_f32_e32 v96, v96
	v_exp_f32_e32 v97, v97
	s_waitcnt vmcnt(3)
	v_mul_f32_e32 v98, 0xbfb8aa3b, v52
	v_mul_f32_e32 v99, 0xbfb8aa3b, v53
	v_rcp_f32_e32 v64, v18
	v_rcp_f32_e32 v65, v67
	v_rcp_f32_e32 v66, v87
	v_rcp_f32_e32 v67, v88
	v_add_f32_e32 v18, 1.0, v71
	v_add_f32_e32 v71, 1.0, v68
	v_add_f32_e32 v87, 1.0, v69
	v_add_f32_e32 v88, 1.0, v70
	v_exp_f32_e32 v98, v98
	v_exp_f32_e32 v99, v99
	v_mul_f32_e32 v102, 0xbfb8aa3b, v10
	v_mul_f32_e32 v103, 0xbfb8aa3b, v11
	v_mul_f32_e32 v104, 0xbfb8aa3b, v12
	v_mul_f32_e32 v105, 0xbfb8aa3b, v13
	v_mul_f32_e32 v100, 0xbfb8aa3b, v54
	v_mul_f32_e32 v101, 0xbfb8aa3b, v55
	v_rcp_f32_e32 v68, v18
	v_rcp_f32_e32 v69, v71
	v_rcp_f32_e32 v70, v87
	v_rcp_f32_e32 v71, v88
	v_add_f32_e32 v18, 1.0, v90
	v_add_f32_e32 v83, 1.0, v83
	v_add_f32_e32 v84, 1.0, v84
	v_add_f32_e32 v85, 1.0, v85
	v_exp_f32_e32 v87, v102
	v_exp_f32_e32 v88, v103
	v_exp_f32_e32 v90, v104
	v_exp_f32_e32 v102, v105
	s_waitcnt vmcnt(2)
	v_mul_f32_e32 v103, 0xbfb8aa3b, v14
	v_mul_f32_e32 v104, 0xbfb8aa3b, v15
	v_mul_f32_e32 v105, 0xbfb8aa3b, v16
	v_mul_f32_e32 v106, 0xbfb8aa3b, v17
	v_exp_f32_e32 v100, v100
	v_exp_f32_e32 v101, v101
	v_pk_mul_f32 v[24:25], v[24:25], v[56:57]
	v_pk_mul_f32 v[26:27], v[26:27], v[58:59]
	v_rcp_f32_e32 v56, v18
	v_rcp_f32_e32 v57, v83
	v_rcp_f32_e32 v58, v84
	v_rcp_f32_e32 v59, v85
	v_add_f32_e32 v18, 1.0, v89
	v_add_f32_e32 v83, 1.0, v91
	v_add_f32_e32 v84, 1.0, v92
	v_add_f32_e32 v85, 1.0, v93
	v_exp_f32_e32 v89, v103
	v_exp_f32_e32 v91, v104
	v_exp_f32_e32 v92, v105
	v_exp_f32_e32 v93, v106
	s_waitcnt vmcnt(1)
	v_mul_f32_e32 v103, 0xbfb8aa3b, v6
	v_mul_f32_e32 v104, 0xbfb8aa3b, v7
	v_mul_f32_e32 v105, 0xbfb8aa3b, v8
	v_mul_f32_e32 v106, 0xbfb8aa3b, v9
	v_pk_mul_f32 v[28:29], v[28:29], v[60:61]
	v_pk_mul_f32 v[30:31], v[30:31], v[62:63]
	v_rcp_f32_e32 v60, v18
	v_rcp_f32_e32 v61, v83
	v_rcp_f32_e32 v62, v84
	v_rcp_f32_e32 v63, v85
	v_add_f32_e32 v18, 1.0, v94
	v_add_f32_e32 v83, 1.0, v95
	v_add_f32_e32 v84, 1.0, v96
	v_add_f32_e32 v85, 1.0, v97
	v_cvt_pk_bf16_f32 v24, v24, v25
	v_cvt_pk_bf16_f32 v25, v26, v27
	v_exp_f32_e32 v94, v103
	v_exp_f32_e32 v95, v104
	v_exp_f32_e32 v96, v105
	v_exp_f32_e32 v97, v106
	s_waitcnt vmcnt(0)
	v_mul_f32_e32 v103, 0xbfb8aa3b, v2
	v_mul_f32_e32 v104, 0xbfb8aa3b, v3
	v_mul_f32_e32 v105, 0xbfb8aa3b, v4
	v_mul_f32_e32 v106, 0xbfb8aa3b, v5
	v_pk_mul_f32 v[26:27], v[32:33], v[64:65]
	v_pk_mul_f32 v[32:33], v[34:35], v[66:67]
	v_rcp_f32_e32 v34, v18
	v_rcp_f32_e32 v35, v83
	v_rcp_f32_e32 v64, v84
	v_rcp_f32_e32 v65, v85
	ds_write_b64 v23, v[24:25]
	v_cvt_pk_bf16_f32 v24, v28, v29
	v_cvt_pk_bf16_f32 v25, v30, v31
	v_add_f32_e32 v18, 1.0, v98
	v_add_f32_e32 v23, 1.0, v99
	v_exp_f32_e32 v83, v103
	v_exp_f32_e32 v84, v104
	v_exp_f32_e32 v85, v105
	v_exp_f32_e32 v98, v106
	v_pk_mul_f32 v[28:29], v[36:37], v[68:69]
	v_pk_mul_f32 v[30:31], v[38:39], v[70:71]
	ds_write_b64 v72, v[24:25]
	v_cvt_pk_bf16_f32 v24, v26, v27
	v_cvt_pk_bf16_f32 v25, v32, v33
	v_rcp_f32_e32 v26, v18
	v_rcp_f32_e32 v27, v23
	v_add_f32_e32 v18, 1.0, v87
	v_add_f32_e32 v23, 1.0, v88
	v_add_f32_e32 v66, 1.0, v100
	v_add_f32_e32 v67, 1.0, v101
	v_pk_mul_f32 v[36:37], v[40:41], v[56:57]
	v_pk_mul_f32 v[38:39], v[42:43], v[58:59]
	ds_write_b64 v73, v[24:25]
	v_cvt_pk_bf16_f32 v24, v28, v29
	v_cvt_pk_bf16_f32 v25, v30, v31
	v_rcp_f32_e32 v28, v18
	v_rcp_f32_e32 v29, v23
	v_add_f32_e32 v18, 1.0, v89
	v_add_f32_e32 v23, 1.0, v91
	v_rcp_f32_e32 v32, v66
	v_rcp_f32_e32 v33, v67
	v_add_f32_e32 v66, 1.0, v90
	v_add_f32_e32 v67, 1.0, v102
	v_pk_mul_f32 v[40:41], v[44:45], v[60:61]
	v_pk_mul_f32 v[42:43], v[46:47], v[62:63]
	ds_write_b64 v74, v[24:25]
	v_cvt_pk_bf16_f32 v24, v36, v37
	v_cvt_pk_bf16_f32 v25, v38, v39
	v_rcp_f32_e32 v36, v18
	v_rcp_f32_e32 v37, v23
	v_add_f32_e32 v18, 1.0, v94
	v_add_f32_e32 v23, 1.0, v95
	v_add_f32_e32 v46, 1.0, v96
	v_add_f32_e32 v47, 1.0, v97
	v_rcp_f32_e32 v30, v66
	v_rcp_f32_e32 v31, v67
	v_add_f32_e32 v56, 1.0, v92
	v_add_f32_e32 v57, 1.0, v93
	v_pk_mul_f32 v[34:35], v[48:49], v[34:35]
	v_pk_mul_f32 v[44:45], v[50:51], v[64:65]
	ds_write_b64 v75, v[24:25]
	v_cvt_pk_bf16_f32 v24, v40, v41
	v_cvt_pk_bf16_f32 v25, v42, v43
	v_rcp_f32_e32 v40, v18
	v_rcp_f32_e32 v41, v23
	v_rcp_f32_e32 v42, v46
	v_rcp_f32_e32 v43, v47
	v_add_f32_e32 v18, 1.0, v83
	v_add_f32_e32 v23, 1.0, v84
	v_add_f32_e32 v46, 1.0, v85
	v_add_f32_e32 v47, 1.0, v98
	v_rcp_f32_e32 v38, v56
	v_rcp_f32_e32 v39, v57
	ds_write_b64 v76, v[24:25]
	v_cvt_pk_bf16_f32 v24, v34, v35
	v_cvt_pk_bf16_f32 v25, v44, v45
	v_rcp_f32_e32 v34, v18
	v_rcp_f32_e32 v35, v23
	v_rcp_f32_e32 v44, v46
	v_rcp_f32_e32 v45, v47
	v_pk_mul_f32 v[26:27], v[52:53], v[26:27]
	v_pk_mul_f32 v[32:33], v[54:55], v[32:33]
	v_pk_mul_f32 v[10:11], v[10:11], v[28:29]
	v_pk_mul_f32 v[12:13], v[12:13], v[30:31]
	ds_write_b64 v77, v[24:25]
	v_cvt_pk_bf16_f32 v24, v26, v27
	v_cvt_pk_bf16_f32 v25, v32, v33
	v_cvt_pk_bf16_f32 v10, v10, v11
	v_cvt_pk_bf16_f32 v11, v12, v13
	v_pk_mul_f32 v[12:13], v[14:15], v[36:37]
	v_pk_mul_f32 v[14:15], v[16:17], v[38:39]
	v_pk_mul_f32 v[6:7], v[6:7], v[40:41]
	v_pk_mul_f32 v[8:9], v[8:9], v[42:43]
	v_pk_mul_f32 v[2:3], v[2:3], v[34:35]
	v_pk_mul_f32 v[4:5], v[4:5], v[44:45]
	ds_write_b64 v78, v[24:25]
	ds_write_b64 v79, v[10:11]
	v_cvt_pk_bf16_f32 v10, v12, v13
	v_cvt_pk_bf16_f32 v11, v14, v15
	v_cvt_pk_bf16_f32 v6, v6, v7
	v_cvt_pk_bf16_f32 v7, v8, v9
	v_cvt_pk_bf16_f32 v2, v2, v3
	v_cvt_pk_bf16_f32 v3, v4, v5
	ds_write_b64 v80, v[10:11]
	ds_write_b64 v81, v[6:7]
	ds_write_b64 v82, v[2:3]
	s_cbranch_scc0 .LBB0_77
	s_load_dwordx2 s[28:29], s[0:1], 0x50
	s_lshl_b32 s30, s33, 6
	s_lshl_b32 s31, s25, 9
	s_add_u32 s30, s30, s31
	v_lshrrev_b32_e32 v107, 4, v86
	v_and_b32_e32 v108, 15, v86
	v_mul_u32_u24_e32 v107, 0x30000, v107
	v_lshl_add_u32 v107, v108, 2, v107
	v_add_u32_e32 v108, 0x6000, v107
	v_add_u32_e32 v109, 0xc000, v107
	v_add_u32_e32 v110, 0x12000, v107
	v_add_u32_e32 v111, 0x18000, v107
	v_add_u32_e32 v112, 0x1e000, v107
	v_add_u32_e32 v113, 0x24000, v107
	v_add_u32_e32 v114, 0x2a000, v107
	s_waitcnt lgkmcnt(0)
	s_add_u32 s28, s28, s30
	s_addc_u32 s29, s29, 0
	global_load_dword v120, v107, s[28:29]
	global_load_dword v121, v108, s[28:29]
	global_load_dword v122, v109, s[28:29]
	global_load_dword v123, v110, s[28:29]
	global_load_dword v124, v111, s[28:29]
	global_load_dword v125, v112, s[28:29]
	global_load_dword v126, v113, s[28:29]
	global_load_dword v127, v114, s[28:29]
	s_add_u32 s28, s28, 0xc0000
	s_addc_u32 s29, s29, 0
	global_load_dword v128, v107, s[28:29]
	global_load_dword v129, v108, s[28:29]
	global_load_dword v130, v109, s[28:29]
	global_load_dword v131, v110, s[28:29]
	global_load_dword v132, v111, s[28:29]
	global_load_dword v133, v112, s[28:29]
	global_load_dword v134, v113, s[28:29]
	global_load_dword v135, v114, s[28:29]
	s_add_u32 s28, s28, 0xc0000
	s_addc_u32 s29, s29, 0
	global_load_dword v136, v107, s[28:29]
	global_load_dword v137, v108, s[28:29]
	global_load_dword v138, v109, s[28:29]
	global_load_dword v139, v110, s[28:29]
	global_load_dword v140, v111, s[28:29]
	global_load_dword v141, v112, s[28:29]
	global_load_dword v142, v113, s[28:29]
	global_load_dword v143, v114, s[28:29]
	s_add_u32 s28, s28, 0xc0000
	s_addc_u32 s29, s29, 0
	global_load_dword v144, v107, s[28:29]
	global_load_dword v145, v108, s[28:29]
	global_load_dword v146, v109, s[28:29]
	global_load_dword v147, v110, s[28:29]
	global_load_dword v148, v111, s[28:29]
	global_load_dword v149, v112, s[28:29]
	global_load_dword v150, v113, s[28:29]
	global_load_dword v151, v114, s[28:29]
	s_add_u32 s28, s28, 0xc0000
	s_addc_u32 s29, s29, 0
	global_load_dword v152, v107, s[28:29]
	global_load_dword v153, v108, s[28:29]
	global_load_dword v154, v109, s[28:29]
	global_load_dword v155, v110, s[28:29]
	global_load_dword v156, v111, s[28:29]
	global_load_dword v157, v112, s[28:29]
	global_load_dword v158, v113, s[28:29]
	global_load_dword v159, v114, s[28:29]
	s_add_u32 s28, s28, 0xc0000
	s_addc_u32 s29, s29, 0
	global_load_dword v160, v107, s[28:29]
	global_load_dword v161, v108, s[28:29]
	global_load_dword v162, v109, s[28:29]
	global_load_dword v163, v110, s[28:29]
	global_load_dword v164, v111, s[28:29]
	global_load_dword v165, v112, s[28:29]
	global_load_dword v166, v113, s[28:29]
	global_load_dword v167, v114, s[28:29]
	s_add_u32 s28, s28, 0xc0000
	s_addc_u32 s29, s29, 0
	global_load_dword v168, v107, s[28:29]
	global_load_dword v169, v108, s[28:29]
	global_load_dword v170, v109, s[28:29]
	global_load_dword v171, v110, s[28:29]
	global_load_dword v172, v111, s[28:29]
	global_load_dword v173, v112, s[28:29]
	global_load_dword v174, v113, s[28:29]
	global_load_dword v175, v114, s[28:29]
	s_add_u32 s28, s28, 0xc0000
	s_addc_u32 s29, s29, 0
	s_lshl_b32 s4, s33, 4
	s_lshl_b32 s5, s25, 7
	s_add_i32 s4, s4, s5
	s_waitcnt lgkmcnt(0)
	s_barrier
	s_ashr_i32 s5, s4, 31
	s_lshl_b64 s[6:7], s[4:5], 2
	v_and_b32_e32 v62, 15, v86
	v_lshrrev_b32_e32 v63, 4, v86
	v_and_b32_e32 v15, 48, v86
	v_mul_u32_u24_e32 v1, 0x810, v62
	v_add_u32_e32 v1, v1, v15
	v_add_u32_e32 v14, 0x10200, v1
	ds_read_b128 v[64:67], v1
	ds_read_b128 v[68:71], v1 offset:33024
	ds_read_b128 v[72:75], v14
	v_mov_b32_e32 v2, 0
	v_mov_b32_e32 v3, 0
	v_mov_b32_e32 v4, 0
	v_mov_b32_e32 v5, 0
	v_mov_b32_e32 v6, 0
	v_mov_b32_e32 v7, 0
	v_mov_b32_e32 v8, 0
	v_mov_b32_e32 v9, 0
	v_mov_b32_e32 v10, 0
	v_mov_b32_e32 v11, 0
	v_mov_b32_e32 v12, 0
	v_mov_b32_e32 v13, 0
	ds_read_b128 v[76:79], v1 offset:64
	ds_read_b128 v[80:83], v1 offset:33088
	ds_read_b128 v[84:87], v14 offset:64
	s_waitcnt vmcnt(48)
	v_cvt_pk_bf16_f32 v176, v120, v121
	v_cvt_pk_bf16_f32 v177, v122, v123
	v_cvt_pk_bf16_f32 v178, v124, v125
	v_cvt_pk_bf16_f32 v179, v126, v127
	global_load_dword v120, v107, s[28:29]
	global_load_dword v121, v108, s[28:29]
	global_load_dword v122, v109, s[28:29]
	global_load_dword v123, v110, s[28:29]
	global_load_dword v124, v111, s[28:29]
	global_load_dword v125, v112, s[28:29]
	global_load_dword v126, v113, s[28:29]
	global_load_dword v127, v114, s[28:29]
	s_add_u32 s28, s28, 0xc0000
	s_addc_u32 s29, s29, 0
	s_waitcnt lgkmcnt(3)
	v_mfma_f32_16x16x32_bf16 v[10:13], v[64:67], v[176:179], v[10:13]
	v_mfma_f32_16x16x32_bf16 v[6:9], v[68:71], v[176:179], v[6:9]
	v_mfma_f32_16x16x32_bf16 v[2:5], v[72:75], v[176:179], v[2:5]
	ds_read_b128 v[64:67], v1 offset:128
	ds_read_b128 v[68:71], v1 offset:33152
	ds_read_b128 v[72:75], v14 offset:128
	s_waitcnt vmcnt(48)
	v_cvt_pk_bf16_f32 v180, v128, v129
	v_cvt_pk_bf16_f32 v181, v130, v131
	v_cvt_pk_bf16_f32 v182, v132, v133
	v_cvt_pk_bf16_f32 v183, v134, v135
	global_load_dword v128, v107, s[28:29]
	global_load_dword v129, v108, s[28:29]
	global_load_dword v130, v109, s[28:29]
	global_load_dword v131, v110, s[28:29]
	global_load_dword v132, v111, s[28:29]
	global_load_dword v133, v112, s[28:29]
	global_load_dword v134, v113, s[28:29]
	global_load_dword v135, v114, s[28:29]
	s_add_u32 s28, s28, 0xc0000
	s_addc_u32 s29, s29, 0
	s_waitcnt lgkmcnt(3)
	v_mfma_f32_16x16x32_bf16 v[10:13], v[76:79], v[180:183], v[10:13]
	v_mfma_f32_16x16x32_bf16 v[6:9], v[80:83], v[180:183], v[6:9]
	v_mfma_f32_16x16x32_bf16 v[2:5], v[84:87], v[180:183], v[2:5]
	ds_read_b128 v[76:79], v1 offset:192
	ds_read_b128 v[80:83], v1 offset:33216
	ds_read_b128 v[84:87], v14 offset:192
	s_waitcnt vmcnt(48)
	v_cvt_pk_bf16_f32 v176, v136, v137
	v_cvt_pk_bf16_f32 v177, v138, v139
	v_cvt_pk_bf16_f32 v178, v140, v141
	v_cvt_pk_bf16_f32 v179, v142, v143
	global_load_dword v136, v107, s[28:29]
	global_load_dword v137, v108, s[28:29]
	global_load_dword v138, v109, s[28:29]
	global_load_dword v139, v110, s[28:29]
	global_load_dword v140, v111, s[28:29]
	global_load_dword v141, v112, s[28:29]
	global_load_dword v142, v113, s[28:29]
	global_load_dword v143, v114, s[28:29]
	s_add_u32 s28, s28, 0xc0000
	s_addc_u32 s29, s29, 0
	s_waitcnt lgkmcnt(3)
	v_mfma_f32_16x16x32_bf16 v[10:13], v[64:67], v[176:179], v[10:13]
	v_mfma_f32_16x16x32_bf16 v[6:9], v[68:71], v[176:179], v[6:9]
	v_mfma_f32_16x16x32_bf16 v[2:5], v[72:75], v[176:179], v[2:5]
	ds_read_b128 v[64:67], v1 offset:256
	ds_read_b128 v[68:71], v1 offset:33280
	ds_read_b128 v[72:75], v14 offset:256
	s_waitcnt vmcnt(48)
	v_cvt_pk_bf16_f32 v180, v144, v145
	v_cvt_pk_bf16_f32 v181, v146, v147
	v_cvt_pk_bf16_f32 v182, v148, v149
	v_cvt_pk_bf16_f32 v183, v150, v151
	global_load_dword v144, v107, s[28:29]
	global_load_dword v145, v108, s[28:29]
	global_load_dword v146, v109, s[28:29]
	global_load_dword v147, v110, s[28:29]
	global_load_dword v148, v111, s[28:29]
	global_load_dword v149, v112, s[28:29]
	global_load_dword v150, v113, s[28:29]
	global_load_dword v151, v114, s[28:29]
	s_add_u32 s28, s28, 0xc0000
	s_addc_u32 s29, s29, 0
	s_waitcnt lgkmcnt(3)
	v_mfma_f32_16x16x32_bf16 v[10:13], v[76:79], v[180:183], v[10:13]
	v_mfma_f32_16x16x32_bf16 v[6:9], v[80:83], v[180:183], v[6:9]
	v_mfma_f32_16x16x32_bf16 v[2:5], v[84:87], v[180:183], v[2:5]
	ds_read_b128 v[76:79], v1 offset:320
	ds_read_b128 v[80:83], v1 offset:33344
	ds_read_b128 v[84:87], v14 offset:320
	s_waitcnt vmcnt(48)
	v_cvt_pk_bf16_f32 v176, v152, v153
	v_cvt_pk_bf16_f32 v177, v154, v155
	v_cvt_pk_bf16_f32 v178, v156, v157
	v_cvt_pk_bf16_f32 v179, v158, v159
	global_load_dword v152, v107, s[28:29]
	global_load_dword v153, v108, s[28:29]
	global_load_dword v154, v109, s[28:29]
	global_load_dword v155, v110, s[28:29]
	global_load_dword v156, v111, s[28:29]
	global_load_dword v157, v112, s[28:29]
	global_load_dword v158, v113, s[28:29]
	global_load_dword v159, v114, s[28:29]
	s_add_u32 s28, s28, 0xc0000
	s_addc_u32 s29, s29, 0
	s_waitcnt lgkmcnt(3)
	v_mfma_f32_16x16x32_bf16 v[10:13], v[64:67], v[176:179], v[10:13]
	v_mfma_f32_16x16x32_bf16 v[6:9], v[68:71], v[176:179], v[6:9]
	v_mfma_f32_16x16x32_bf16 v[2:5], v[72:75], v[176:179], v[2:5]
	ds_read_b128 v[64:67], v1 offset:384
	ds_read_b128 v[68:71], v1 offset:33408
	ds_read_b128 v[72:75], v14 offset:384
	s_waitcnt vmcnt(48)
	v_cvt_pk_bf16_f32 v180, v160, v161
	v_cvt_pk_bf16_f32 v181, v162, v163
	v_cvt_pk_bf16_f32 v182, v164, v165
	v_cvt_pk_bf16_f32 v183, v166, v167
	global_load_dword v160, v107, s[28:29]
	global_load_dword v161, v108, s[28:29]
	global_load_dword v162, v109, s[28:29]
	global_load_dword v163, v110, s[28:29]
	global_load_dword v164, v111, s[28:29]
	global_load_dword v165, v112, s[28:29]
	global_load_dword v166, v113, s[28:29]
	global_load_dword v167, v114, s[28:29]
	s_add_u32 s28, s28, 0xc0000
	s_addc_u32 s29, s29, 0
	s_waitcnt lgkmcnt(3)
	v_mfma_f32_16x16x32_bf16 v[10:13], v[76:79], v[180:183], v[10:13]
	v_mfma_f32_16x16x32_bf16 v[6:9], v[80:83], v[180:183], v[6:9]
	v_mfma_f32_16x16x32_bf16 v[2:5], v[84:87], v[180:183], v[2:5]
	ds_read_b128 v[76:79], v1 offset:448
	ds_read_b128 v[80:83], v1 offset:33472
	ds_read_b128 v[84:87], v14 offset:448
	s_waitcnt vmcnt(48)
	v_cvt_pk_bf16_f32 v176, v168, v169
	v_cvt_pk_bf16_f32 v177, v170, v171
	v_cvt_pk_bf16_f32 v178, v172, v173
	v_cvt_pk_bf16_f32 v179, v174, v175
	global_load_dword v168, v107, s[28:29]
	global_load_dword v169, v108, s[28:29]
	global_load_dword v170, v109, s[28:29]
	global_load_dword v171, v110, s[28:29]
	global_load_dword v172, v111, s[28:29]
	global_load_dword v173, v112, s[28:29]
	global_load_dword v174, v113, s[28:29]
	global_load_dword v175, v114, s[28:29]
	s_add_u32 s28, s28, 0xc0000
	s_addc_u32 s29, s29, 0
	s_waitcnt lgkmcnt(3)
	v_mfma_f32_16x16x32_bf16 v[10:13], v[64:67], v[176:179], v[10:13]
	v_mfma_f32_16x16x32_bf16 v[6:9], v[68:71], v[176:179], v[6:9]
	v_mfma_f32_16x16x32_bf16 v[2:5], v[72:75], v[176:179], v[2:5]
	ds_read_b128 v[64:67], v1 offset:512
	ds_read_b128 v[68:71], v1 offset:33536
	ds_read_b128 v[72:75], v14 offset:512
	s_waitcnt vmcnt(48)
	v_cvt_pk_bf16_f32 v180, v120, v121
	v_cvt_pk_bf16_f32 v181, v122, v123
	v_cvt_pk_bf16_f32 v182, v124, v125
	v_cvt_pk_bf16_f32 v183, v126, v127
	global_load_dword v120, v107, s[28:29]
	global_load_dword v121, v108, s[28:29]
	global_load_dword v122, v109, s[28:29]
	global_load_dword v123, v110, s[28:29]
	global_load_dword v124, v111, s[28:29]
	global_load_dword v125, v112, s[28:29]
	global_load_dword v126, v113, s[28:29]
	global_load_dword v127, v114, s[28:29]
	s_add_u32 s28, s28, 0xc0000
	s_addc_u32 s29, s29, 0
	s_waitcnt lgkmcnt(3)
	v_mfma_f32_16x16x32_bf16 v[10:13], v[76:79], v[180:183], v[10:13]
	v_mfma_f32_16x16x32_bf16 v[6:9], v[80:83], v[180:183], v[6:9]
	v_mfma_f32_16x16x32_bf16 v[2:5], v[84:87], v[180:183], v[2:5]
	ds_read_b128 v[76:79], v1 offset:576
	ds_read_b128 v[80:83], v1 offset:33600
	ds_read_b128 v[84:87], v14 offset:576
	s_waitcnt vmcnt(48)
	v_cvt_pk_bf16_f32 v176, v128, v129
	v_cvt_pk_bf16_f32 v177, v130, v131
	v_cvt_pk_bf16_f32 v178, v132, v133
	v_cvt_pk_bf16_f32 v179, v134, v135
	global_load_dword v128, v107, s[28:29]
	global_load_dword v129, v108, s[28:29]
	global_load_dword v130, v109, s[28:29]
	global_load_dword v131, v110, s[28:29]
	global_load_dword v132, v111, s[28:29]
	global_load_dword v133, v112, s[28:29]
	global_load_dword v134, v113, s[28:29]
	global_load_dword v135, v114, s[28:29]
	s_add_u32 s28, s28, 0xc0000
	s_addc_u32 s29, s29, 0
	s_waitcnt lgkmcnt(3)
	v_mfma_f32_16x16x32_bf16 v[10:13], v[64:67], v[176:179], v[10:13]
	v_mfma_f32_16x16x32_bf16 v[6:9], v[68:71], v[176:179], v[6:9]
	v_mfma_f32_16x16x32_bf16 v[2:5], v[72:75], v[176:179], v[2:5]
	ds_read_b128 v[64:67], v1 offset:640
	ds_read_b128 v[68:71], v1 offset:33664
	ds_read_b128 v[72:75], v14 offset:640
	s_waitcnt vmcnt(48)
	v_cvt_pk_bf16_f32 v180, v136, v137
	v_cvt_pk_bf16_f32 v181, v138, v139
	v_cvt_pk_bf16_f32 v182, v140, v141
	v_cvt_pk_bf16_f32 v183, v142, v143
	global_load_dword v136, v107, s[28:29]
	global_load_dword v137, v108, s[28:29]
	global_load_dword v138, v109, s[28:29]
	global_load_dword v139, v110, s[28:29]
	global_load_dword v140, v111, s[28:29]
	global_load_dword v141, v112, s[28:29]
	global_load_dword v142, v113, s[28:29]
	global_load_dword v143, v114, s[28:29]
	s_add_u32 s28, s28, 0xc0000
	s_addc_u32 s29, s29, 0
	s_waitcnt lgkmcnt(3)
	v_mfma_f32_16x16x32_bf16 v[10:13], v[76:79], v[180:183], v[10:13]
	v_mfma_f32_16x16x32_bf16 v[6:9], v[80:83], v[180:183], v[6:9]
	v_mfma_f32_16x16x32_bf16 v[2:5], v[84:87], v[180:183], v[2:5]
	ds_read_b128 v[76:79], v1 offset:704
	ds_read_b128 v[80:83], v1 offset:33728
	ds_read_b128 v[84:87], v14 offset:704
	s_waitcnt vmcnt(48)
	v_cvt_pk_bf16_f32 v176, v144, v145
	v_cvt_pk_bf16_f32 v177, v146, v147
	v_cvt_pk_bf16_f32 v178, v148, v149
	v_cvt_pk_bf16_f32 v179, v150, v151
	global_load_dword v144, v107, s[28:29]
	global_load_dword v145, v108, s[28:29]
	global_load_dword v146, v109, s[28:29]
	global_load_dword v147, v110, s[28:29]
	global_load_dword v148, v111, s[28:29]
	global_load_dword v149, v112, s[28:29]
	global_load_dword v150, v113, s[28:29]
	global_load_dword v151, v114, s[28:29]
	s_add_u32 s28, s28, 0xc0000
	s_addc_u32 s29, s29, 0
	s_waitcnt lgkmcnt(3)
	v_mfma_f32_16x16x32_bf16 v[10:13], v[64:67], v[176:179], v[10:13]
	v_mfma_f32_16x16x32_bf16 v[6:9], v[68:71], v[176:179], v[6:9]
	v_mfma_f32_16x16x32_bf16 v[2:5], v[72:75], v[176:179], v[2:5]
	ds_read_b128 v[64:67], v1 offset:768
	ds_read_b128 v[68:71], v1 offset:33792
	ds_read_b128 v[72:75], v14 offset:768
	s_waitcnt vmcnt(48)
	v_cvt_pk_bf16_f32 v180, v152, v153
	v_cvt_pk_bf16_f32 v181, v154, v155
	v_cvt_pk_bf16_f32 v182, v156, v157
	v_cvt_pk_bf16_f32 v183, v158, v159
	global_load_dword v152, v107, s[28:29]
	global_load_dword v153, v108, s[28:29]
	global_load_dword v154, v109, s[28:29]
	global_load_dword v155, v110, s[28:29]
	global_load_dword v156, v111, s[28:29]
	global_load_dword v157, v112, s[28:29]
	global_load_dword v158, v113, s[28:29]
	global_load_dword v159, v114, s[28:29]
	s_add_u32 s28, s28, 0xc0000
	s_addc_u32 s29, s29, 0
	s_waitcnt lgkmcnt(3)
	v_mfma_f32_16x16x32_bf16 v[10:13], v[76:79], v[180:183], v[10:13]
	v_mfma_f32_16x16x32_bf16 v[6:9], v[80:83], v[180:183], v[6:9]
	v_mfma_f32_16x16x32_bf16 v[2:5], v[84:87], v[180:183], v[2:5]
	ds_read_b128 v[76:79], v1 offset:832
	ds_read_b128 v[80:83], v1 offset:33856
	ds_read_b128 v[84:87], v14 offset:832
	s_waitcnt vmcnt(48)
	v_cvt_pk_bf16_f32 v176, v160, v161
	v_cvt_pk_bf16_f32 v177, v162, v163
	v_cvt_pk_bf16_f32 v178, v164, v165
	v_cvt_pk_bf16_f32 v179, v166, v167
	global_load_dword v160, v107, s[28:29]
	global_load_dword v161, v108, s[28:29]
	global_load_dword v162, v109, s[28:29]
	global_load_dword v163, v110, s[28:29]
	global_load_dword v164, v111, s[28:29]
	global_load_dword v165, v112, s[28:29]
	global_load_dword v166, v113, s[28:29]
	global_load_dword v167, v114, s[28:29]
	s_add_u32 s28, s28, 0xc0000
	s_addc_u32 s29, s29, 0
	s_waitcnt lgkmcnt(3)
	v_mfma_f32_16x16x32_bf16 v[10:13], v[64:67], v[176:179], v[10:13]
	v_mfma_f32_16x16x32_bf16 v[6:9], v[68:71], v[176:179], v[6:9]
	v_mfma_f32_16x16x32_bf16 v[2:5], v[72:75], v[176:179], v[2:5]
	ds_read_b128 v[64:67], v1 offset:896
	ds_read_b128 v[68:71], v1 offset:33920
	ds_read_b128 v[72:75], v14 offset:896
	s_waitcnt vmcnt(48)
	v_cvt_pk_bf16_f32 v180, v168, v169
	v_cvt_pk_bf16_f32 v181, v170, v171
	v_cvt_pk_bf16_f32 v182, v172, v173
	v_cvt_pk_bf16_f32 v183, v174, v175
	global_load_dword v168, v107, s[28:29]
	global_load_dword v169, v108, s[28:29]
	global_load_dword v170, v109, s[28:29]
	global_load_dword v171, v110, s[28:29]
	global_load_dword v172, v111, s[28:29]
	global_load_dword v173, v112, s[28:29]
	global_load_dword v174, v113, s[28:29]
	global_load_dword v175, v114, s[28:29]
	s_add_u32 s28, s28, 0xc0000
	s_addc_u32 s29, s29, 0
	s_waitcnt lgkmcnt(3)
	v_mfma_f32_16x16x32_bf16 v[10:13], v[76:79], v[180:183], v[10:13]
	v_mfma_f32_16x16x32_bf16 v[6:9], v[80:83], v[180:183], v[6:9]
	v_mfma_f32_16x16x32_bf16 v[2:5], v[84:87], v[180:183], v[2:5]
	ds_read_b128 v[76:79], v1 offset:960
	ds_read_b128 v[80:83], v1 offset:33984
	ds_read_b128 v[84:87], v14 offset:960
	s_waitcnt vmcnt(48)
	v_cvt_pk_bf16_f32 v176, v120, v121
	v_cvt_pk_bf16_f32 v177, v122, v123
	v_cvt_pk_bf16_f32 v178, v124, v125
	v_cvt_pk_bf16_f32 v179, v126, v127
	global_load_dword v120, v107, s[28:29]
	global_load_dword v121, v108, s[28:29]
	global_load_dword v122, v109, s[28:29]
	global_load_dword v123, v110, s[28:29]
	global_load_dword v124, v111, s[28:29]
	global_load_dword v125, v112, s[28:29]
	global_load_dword v126, v113, s[28:29]
	global_load_dword v127, v114, s[28:29]
	s_add_u32 s28, s28, 0xc0000
	s_addc_u32 s29, s29, 0
	s_waitcnt lgkmcnt(3)
	v_mfma_f32_16x16x32_bf16 v[10:13], v[64:67], v[176:179], v[10:13]
	v_mfma_f32_16x16x32_bf16 v[6:9], v[68:71], v[176:179], v[6:9]
	v_mfma_f32_16x16x32_bf16 v[2:5], v[72:75], v[176:179], v[2:5]
	ds_read_b128 v[64:67], v1 offset:1024
	ds_read_b128 v[68:71], v1 offset:34048
	ds_read_b128 v[72:75], v14 offset:1024
	s_waitcnt vmcnt(48)
	v_cvt_pk_bf16_f32 v180, v128, v129
	v_cvt_pk_bf16_f32 v181, v130, v131
	v_cvt_pk_bf16_f32 v182, v132, v133
	v_cvt_pk_bf16_f32 v183, v134, v135
	global_load_dword v128, v107, s[28:29]
	global_load_dword v129, v108, s[28:29]
	global_load_dword v130, v109, s[28:29]
	global_load_dword v131, v110, s[28:29]
	global_load_dword v132, v111, s[28:29]
	global_load_dword v133, v112, s[28:29]
	global_load_dword v134, v113, s[28:29]
	global_load_dword v135, v114, s[28:29]
	s_add_u32 s28, s28, 0xc0000
	s_addc_u32 s29, s29, 0
	s_waitcnt lgkmcnt(3)
	v_mfma_f32_16x16x32_bf16 v[10:13], v[76:79], v[180:183], v[10:13]
	v_mfma_f32_16x16x32_bf16 v[6:9], v[80:83], v[180:183], v[6:9]
	v_mfma_f32_16x16x32_bf16 v[2:5], v[84:87], v[180:183], v[2:5]
	ds_read_b128 v[76:79], v1 offset:1088
	ds_read_b128 v[80:83], v1 offset:34112
	ds_read_b128 v[84:87], v14 offset:1088
	s_waitcnt vmcnt(48)
	v_cvt_pk_bf16_f32 v176, v136, v137
	v_cvt_pk_bf16_f32 v177, v138, v139
	v_cvt_pk_bf16_f32 v178, v140, v141
	v_cvt_pk_bf16_f32 v179, v142, v143
	global_load_dword v136, v107, s[28:29]
	global_load_dword v137, v108, s[28:29]
	global_load_dword v138, v109, s[28:29]
	global_load_dword v139, v110, s[28:29]
	global_load_dword v140, v111, s[28:29]
	global_load_dword v141, v112, s[28:29]
	global_load_dword v142, v113, s[28:29]
	global_load_dword v143, v114, s[28:29]
	s_add_u32 s28, s28, 0xc0000
	s_addc_u32 s29, s29, 0
	s_waitcnt lgkmcnt(3)
	v_mfma_f32_16x16x32_bf16 v[10:13], v[64:67], v[176:179], v[10:13]
	v_mfma_f32_16x16x32_bf16 v[6:9], v[68:71], v[176:179], v[6:9]
	v_mfma_f32_16x16x32_bf16 v[2:5], v[72:75], v[176:179], v[2:5]
	ds_read_b128 v[64:67], v1 offset:1152
	ds_read_b128 v[68:71], v1 offset:34176
	ds_read_b128 v[72:75], v14 offset:1152
	s_waitcnt vmcnt(48)
	v_cvt_pk_bf16_f32 v180, v144, v145
	v_cvt_pk_bf16_f32 v181, v146, v147
	v_cvt_pk_bf16_f32 v182, v148, v149
	v_cvt_pk_bf16_f32 v183, v150, v151
	global_load_dword v144, v107, s[28:29]
	global_load_dword v145, v108, s[28:29]
	global_load_dword v146, v109, s[28:29]
	global_load_dword v147, v110, s[28:29]
	global_load_dword v148, v111, s[28:29]
	global_load_dword v149, v112, s[28:29]
	global_load_dword v150, v113, s[28:29]
	global_load_dword v151, v114, s[28:29]
	s_add_u32 s28, s28, 0xc0000
	s_addc_u32 s29, s29, 0
	s_waitcnt lgkmcnt(3)
	v_mfma_f32_16x16x32_bf16 v[10:13], v[76:79], v[180:183], v[10:13]
	v_mfma_f32_16x16x32_bf16 v[6:9], v[80:83], v[180:183], v[6:9]
	v_mfma_f32_16x16x32_bf16 v[2:5], v[84:87], v[180:183], v[2:5]
	ds_read_b128 v[76:79], v1 offset:1216
	ds_read_b128 v[80:83], v1 offset:34240
	ds_read_b128 v[84:87], v14 offset:1216
	s_waitcnt vmcnt(48)
	v_cvt_pk_bf16_f32 v176, v152, v153
	v_cvt_pk_bf16_f32 v177, v154, v155
	v_cvt_pk_bf16_f32 v178, v156, v157
	v_cvt_pk_bf16_f32 v179, v158, v159
	global_load_dword v152, v107, s[28:29]
	global_load_dword v153, v108, s[28:29]
	global_load_dword v154, v109, s[28:29]
	global_load_dword v155, v110, s[28:29]
	global_load_dword v156, v111, s[28:29]
	global_load_dword v157, v112, s[28:29]
	global_load_dword v158, v113, s[28:29]
	global_load_dword v159, v114, s[28:29]
	s_add_u32 s28, s28, 0xc0000
	s_addc_u32 s29, s29, 0
	s_waitcnt lgkmcnt(3)
	v_mfma_f32_16x16x32_bf16 v[10:13], v[64:67], v[176:179], v[10:13]
	v_mfma_f32_16x16x32_bf16 v[6:9], v[68:71], v[176:179], v[6:9]
	v_mfma_f32_16x16x32_bf16 v[2:5], v[72:75], v[176:179], v[2:5]
	ds_read_b128 v[64:67], v1 offset:1280
	ds_read_b128 v[68:71], v1 offset:34304
	ds_read_b128 v[72:75], v14 offset:1280
	s_waitcnt vmcnt(48)
	v_cvt_pk_bf16_f32 v180, v160, v161
	v_cvt_pk_bf16_f32 v181, v162, v163
	v_cvt_pk_bf16_f32 v182, v164, v165
	v_cvt_pk_bf16_f32 v183, v166, v167
	global_load_dword v160, v107, s[28:29]
	global_load_dword v161, v108, s[28:29]
	global_load_dword v162, v109, s[28:29]
	global_load_dword v163, v110, s[28:29]
	global_load_dword v164, v111, s[28:29]
	global_load_dword v165, v112, s[28:29]
	global_load_dword v166, v113, s[28:29]
	global_load_dword v167, v114, s[28:29]
	s_add_u32 s28, s28, 0xc0000
	s_addc_u32 s29, s29, 0
	s_waitcnt lgkmcnt(3)
	v_mfma_f32_16x16x32_bf16 v[10:13], v[76:79], v[180:183], v[10:13]
	v_mfma_f32_16x16x32_bf16 v[6:9], v[80:83], v[180:183], v[6:9]
	v_mfma_f32_16x16x32_bf16 v[2:5], v[84:87], v[180:183], v[2:5]
	ds_read_b128 v[76:79], v1 offset:1344
	ds_read_b128 v[80:83], v1 offset:34368
	ds_read_b128 v[84:87], v14 offset:1344
	s_waitcnt vmcnt(48)
	v_cvt_pk_bf16_f32 v176, v168, v169
	v_cvt_pk_bf16_f32 v177, v170, v171
	v_cvt_pk_bf16_f32 v178, v172, v173
	v_cvt_pk_bf16_f32 v179, v174, v175
	global_load_dword v168, v107, s[28:29]
	global_load_dword v169, v108, s[28:29]
	global_load_dword v170, v109, s[28:29]
	global_load_dword v171, v110, s[28:29]
	global_load_dword v172, v111, s[28:29]
	global_load_dword v173, v112, s[28:29]
	global_load_dword v174, v113, s[28:29]
	global_load_dword v175, v114, s[28:29]
	s_add_u32 s28, s28, 0xc0000
	s_addc_u32 s29, s29, 0
	s_waitcnt lgkmcnt(3)
	v_mfma_f32_16x16x32_bf16 v[10:13], v[64:67], v[176:179], v[10:13]
	v_mfma_f32_16x16x32_bf16 v[6:9], v[68:71], v[176:179], v[6:9]
	v_mfma_f32_16x16x32_bf16 v[2:5], v[72:75], v[176:179], v[2:5]
	ds_read_b128 v[64:67], v1 offset:1408
	ds_read_b128 v[68:71], v1 offset:34432
	ds_read_b128 v[72:75], v14 offset:1408
	s_waitcnt vmcnt(48)
	v_cvt_pk_bf16_f32 v180, v120, v121
	v_cvt_pk_bf16_f32 v181, v122, v123
	v_cvt_pk_bf16_f32 v182, v124, v125
	v_cvt_pk_bf16_f32 v183, v126, v127
	global_load_dword v120, v107, s[28:29]
	global_load_dword v121, v108, s[28:29]
	global_load_dword v122, v109, s[28:29]
	global_load_dword v123, v110, s[28:29]
	global_load_dword v124, v111, s[28:29]
	global_load_dword v125, v112, s[28:29]
	global_load_dword v126, v113, s[28:29]
	global_load_dword v127, v114, s[28:29]
	s_add_u32 s28, s28, 0xc0000
	s_addc_u32 s29, s29, 0
	s_waitcnt lgkmcnt(3)
	v_mfma_f32_16x16x32_bf16 v[10:13], v[76:79], v[180:183], v[10:13]
	v_mfma_f32_16x16x32_bf16 v[6:9], v[80:83], v[180:183], v[6:9]
	v_mfma_f32_16x16x32_bf16 v[2:5], v[84:87], v[180:183], v[2:5]
	ds_read_b128 v[76:79], v1 offset:1472
	ds_read_b128 v[80:83], v1 offset:34496
	ds_read_b128 v[84:87], v14 offset:1472
	s_waitcnt vmcnt(48)
	v_cvt_pk_bf16_f32 v176, v128, v129
	v_cvt_pk_bf16_f32 v177, v130, v131
	v_cvt_pk_bf16_f32 v178, v132, v133
	v_cvt_pk_bf16_f32 v179, v134, v135
	global_load_dword v128, v107, s[28:29]
	global_load_dword v129, v108, s[28:29]
	global_load_dword v130, v109, s[28:29]
	global_load_dword v131, v110, s[28:29]
	global_load_dword v132, v111, s[28:29]
	global_load_dword v133, v112, s[28:29]
	global_load_dword v134, v113, s[28:29]
	global_load_dword v135, v114, s[28:29]
	s_add_u32 s28, s28, 0xc0000
	s_addc_u32 s29, s29, 0
	s_waitcnt lgkmcnt(3)
	v_mfma_f32_16x16x32_bf16 v[10:13], v[64:67], v[176:179], v[10:13]
	v_mfma_f32_16x16x32_bf16 v[6:9], v[68:71], v[176:179], v[6:9]
	v_mfma_f32_16x16x32_bf16 v[2:5], v[72:75], v[176:179], v[2:5]
	ds_read_b128 v[64:67], v1 offset:1536
	ds_read_b128 v[68:71], v1 offset:34560
	ds_read_b128 v[72:75], v14 offset:1536
	s_waitcnt vmcnt(48)
	v_cvt_pk_bf16_f32 v180, v136, v137
	v_cvt_pk_bf16_f32 v181, v138, v139
	v_cvt_pk_bf16_f32 v182, v140, v141
	v_cvt_pk_bf16_f32 v183, v142, v143
	global_load_dword v136, v107, s[28:29]
	global_load_dword v137, v108, s[28:29]
	global_load_dword v138, v109, s[28:29]
	global_load_dword v139, v110, s[28:29]
	global_load_dword v140, v111, s[28:29]
	global_load_dword v141, v112, s[28:29]
	global_load_dword v142, v113, s[28:29]
	global_load_dword v143, v114, s[28:29]
	s_add_u32 s28, s28, 0xc0000
	s_addc_u32 s29, s29, 0
	s_waitcnt lgkmcnt(3)
	v_mfma_f32_16x16x32_bf16 v[10:13], v[76:79], v[180:183], v[10:13]
	v_mfma_f32_16x16x32_bf16 v[6:9], v[80:83], v[180:183], v[6:9]
	v_mfma_f32_16x16x32_bf16 v[2:5], v[84:87], v[180:183], v[2:5]
	ds_read_b128 v[76:79], v1 offset:1600
	ds_read_b128 v[80:83], v1 offset:34624
	ds_read_b128 v[84:87], v14 offset:1600
	s_waitcnt vmcnt(48)
	v_cvt_pk_bf16_f32 v176, v144, v145
	v_cvt_pk_bf16_f32 v177, v146, v147
	v_cvt_pk_bf16_f32 v178, v148, v149
	v_cvt_pk_bf16_f32 v179, v150, v151
	global_load_dword v144, v107, s[28:29]
	global_load_dword v145, v108, s[28:29]
	global_load_dword v146, v109, s[28:29]
	global_load_dword v147, v110, s[28:29]
	global_load_dword v148, v111, s[28:29]
	global_load_dword v149, v112, s[28:29]
	global_load_dword v150, v113, s[28:29]
	global_load_dword v151, v114, s[28:29]
	s_add_u32 s28, s28, 0xc0000
	s_addc_u32 s29, s29, 0
	s_waitcnt lgkmcnt(3)
	v_mfma_f32_16x16x32_bf16 v[10:13], v[64:67], v[176:179], v[10:13]
	v_mfma_f32_16x16x32_bf16 v[6:9], v[68:71], v[176:179], v[6:9]
	v_mfma_f32_16x16x32_bf16 v[2:5], v[72:75], v[176:179], v[2:5]
	ds_read_b128 v[64:67], v1 offset:1664
	ds_read_b128 v[68:71], v1 offset:34688
	ds_read_b128 v[72:75], v14 offset:1664
	s_waitcnt vmcnt(48)
	v_cvt_pk_bf16_f32 v180, v152, v153
	v_cvt_pk_bf16_f32 v181, v154, v155
	v_cvt_pk_bf16_f32 v182, v156, v157
	v_cvt_pk_bf16_f32 v183, v158, v159
	s_nop 1
	s_waitcnt lgkmcnt(3)
	v_mfma_f32_16x16x32_bf16 v[10:13], v[76:79], v[180:183], v[10:13]
	v_mfma_f32_16x16x32_bf16 v[6:9], v[80:83], v[180:183], v[6:9]
	v_mfma_f32_16x16x32_bf16 v[2:5], v[84:87], v[180:183], v[2:5]
	ds_read_b128 v[76:79], v1 offset:1728
	ds_read_b128 v[80:83], v1 offset:34752
	ds_read_b128 v[84:87], v14 offset:1728
	s_waitcnt vmcnt(40)
	v_cvt_pk_bf16_f32 v176, v160, v161
	v_cvt_pk_bf16_f32 v177, v162, v163
	v_cvt_pk_bf16_f32 v178, v164, v165
	v_cvt_pk_bf16_f32 v179, v166, v167
	s_nop 1
	s_waitcnt lgkmcnt(3)
	v_mfma_f32_16x16x32_bf16 v[10:13], v[64:67], v[176:179], v[10:13]
	v_mfma_f32_16x16x32_bf16 v[6:9], v[68:71], v[176:179], v[6:9]
	v_mfma_f32_16x16x32_bf16 v[2:5], v[72:75], v[176:179], v[2:5]
	ds_read_b128 v[64:67], v1 offset:1792
	ds_read_b128 v[68:71], v1 offset:34816
	ds_read_b128 v[72:75], v14 offset:1792
	s_waitcnt vmcnt(32)
	v_cvt_pk_bf16_f32 v180, v168, v169
	v_cvt_pk_bf16_f32 v181, v170, v171
	v_cvt_pk_bf16_f32 v182, v172, v173
	v_cvt_pk_bf16_f32 v183, v174, v175
	s_nop 1
	s_waitcnt lgkmcnt(3)
	v_mfma_f32_16x16x32_bf16 v[10:13], v[76:79], v[180:183], v[10:13]
	v_mfma_f32_16x16x32_bf16 v[6:9], v[80:83], v[180:183], v[6:9]
	v_mfma_f32_16x16x32_bf16 v[2:5], v[84:87], v[180:183], v[2:5]
	ds_read_b128 v[76:79], v1 offset:1856
	ds_read_b128 v[80:83], v1 offset:34880
	ds_read_b128 v[84:87], v14 offset:1856
	s_waitcnt vmcnt(24)
	v_cvt_pk_bf16_f32 v176, v120, v121
	v_cvt_pk_bf16_f32 v177, v122, v123
	v_cvt_pk_bf16_f32 v178, v124, v125
	v_cvt_pk_bf16_f32 v179, v126, v127
	s_nop 1
	s_waitcnt lgkmcnt(3)
	v_mfma_f32_16x16x32_bf16 v[10:13], v[64:67], v[176:179], v[10:13]
	v_mfma_f32_16x16x32_bf16 v[6:9], v[68:71], v[176:179], v[6:9]
	v_mfma_f32_16x16x32_bf16 v[2:5], v[72:75], v[176:179], v[2:5]
	ds_read_b128 v[64:67], v1 offset:1920
	ds_read_b128 v[68:71], v1 offset:34944
	ds_read_b128 v[72:75], v14 offset:1920
	s_waitcnt vmcnt(16)
	v_cvt_pk_bf16_f32 v180, v128, v129
	v_cvt_pk_bf16_f32 v181, v130, v131
	v_cvt_pk_bf16_f32 v182, v132, v133
	v_cvt_pk_bf16_f32 v183, v134, v135
	s_nop 1
	s_waitcnt lgkmcnt(3)
	v_mfma_f32_16x16x32_bf16 v[10:13], v[76:79], v[180:183], v[10:13]
	v_mfma_f32_16x16x32_bf16 v[6:9], v[80:83], v[180:183], v[6:9]
	v_mfma_f32_16x16x32_bf16 v[2:5], v[84:87], v[180:183], v[2:5]
	ds_read_b128 v[76:79], v1 offset:1984
	ds_read_b128 v[80:83], v1 offset:35008
	ds_read_b128 v[84:87], v14 offset:1984
	s_waitcnt vmcnt(8)
	v_cvt_pk_bf16_f32 v176, v136, v137
	v_cvt_pk_bf16_f32 v177, v138, v139
	v_cvt_pk_bf16_f32 v178, v140, v141
	v_cvt_pk_bf16_f32 v179, v142, v143
	s_nop 1
	s_waitcnt lgkmcnt(3)
	v_mfma_f32_16x16x32_bf16 v[10:13], v[64:67], v[176:179], v[10:13]
	v_mfma_f32_16x16x32_bf16 v[6:9], v[68:71], v[176:179], v[6:9]
	v_mfma_f32_16x16x32_bf16 v[2:5], v[72:75], v[176:179], v[2:5]
	s_waitcnt vmcnt(0)
	v_cvt_pk_bf16_f32 v180, v144, v145
	v_cvt_pk_bf16_f32 v181, v146, v147
	v_cvt_pk_bf16_f32 v182, v148, v149
	v_cvt_pk_bf16_f32 v183, v150, v151
	s_nop 1
	s_waitcnt lgkmcnt(0)
	v_mfma_f32_16x16x32_bf16 v[10:13], v[76:79], v[180:183], v[10:13]
	v_mfma_f32_16x16x32_bf16 v[6:9], v[80:83], v[180:183], v[6:9]
	v_mfma_f32_16x16x32_bf16 v[2:5], v[84:87], v[180:183], v[2:5]
	s_nop 7
	s_load_dwordx2 s[8:9], s[0:1], 0x58
	v_or_b32_e32 v14, s4, v62
	v_ashrrev_i32_e32 v15, 31, v14
	s_add_u32 s4, s74, s6
	s_addc_u32 s5, s75, s7
	s_waitcnt lgkmcnt(0)
	v_lshl_add_u64 v[14:15], v[14:15], 2, s[8:9]
	global_load_dword v16, v[14:15], off
	v_lshlrev_b32_e32 v14, 2, v62
	v_mov_b32_e32 v15, 0
	v_lshl_or_b32 v1, v63, 2, s24
	v_lshl_add_u64 v[14:15], s[4:5], 0, v[14:15]
	s_mov_b64 s[4:5], 0x2380000
	s_movk_i32 s6, 0x82
	v_lshl_add_u64 v[14:15], v[14:15], 0, s[4:5]
	v_cmp_gt_i32_e32 vcc, s6, v1
	s_and_saveexec_b64 s[4:5], vcc
	s_cbranch_execz .LBB0_82
	s_movk_i32 s7, 0x6000
	v_mul_lo_u32 v18, v1, s7
	v_ashrrev_i32_e32 v19, 31, v18
	s_waitcnt vmcnt(0)
	v_add_f32_e32 v10, v10, v16
	v_lshl_add_u64 v[18:19], v[14:15], 0, v[18:19]
	global_store_dword v[18:19], v10, off
